# BRANCH: DMA prologue of each GEMM issued after the register epilogue instead of before it
# baseline (speedup 1.0000x reference)
; #define BLOAD(A_, B_, kt) do { _Pragma("unroll") for (int i = 0; i < 4; ++i) { \
;     A_[i] = *(const u32x4*)((const char*)Ap + (aoff + (unsigned)(32 * i * lda + (kt) * 64) * 2u)); B_[i] = *(const u32x4*)((const char*)Wt + (woff + (unsigned)(32 * i * K + (kt) * 64) * 2u)); } } while (0)
; #define BLOAD(A_, B_, kt) do { _Pragma("unroll") for (int i = 0; i < 4; ++i) { \
;     A_[i] = *(const u32x4*)((const char*)Ap + (aoff + (unsigned)(32 * i * lda + (kt) * 64) * 2u)); B_[i] = *(const u32x4*)((const char*)Wt + (woff + (unsigned)(32 * i * K + (kt) * 64) * 2u)); } } while (0)
; #define BSTORE(A_, B_, buf) do { _Pragma("unroll") for (int i = 0; i < 4; ++i) { \
;     *(u32x4*)&As[(buf) * GBUF + (srow + 32 * i) * LDT + sc8] = A_[i]; \
;     *(u32x4*)&Bs[(buf) * GBUF + (srow + 32 * i) * LDT + sc8] = B_[i]; } } while (0)
; template <bool ROWNORM, int NK>
; DI void gemm_main_bf(const u16* __restrict__ Ap, int lda, const u16* __restrict__ Wt, f32x16 (&acc)[2][2], char* smem, float* rinv_s) {
;     ...
;   __builtin_amdgcn_s_setprio(0);
;   BLOAD(a0, b0, 0); BLOAD(a1, b1, 1);
;   __syncthreads();
;   BSTORE(a0, b0, 0);
;   BLOAD(a0, b0, 2);
;   __syncthreads();
; #pragma unroll
;   for (int kt = 0; kt < nk; kt += 2) {
;     BCOMP(0);
;     BSTORE(a1, b1, 1);
;     if (kt + 3 < nk) BLOAD(a1, b1, kt + 3);
;     __syncthreads();
;     BCOMP(1);
;     if (kt + 2 < nk) { BSTORE(a0, b0, 0); if (kt + 4 < nk) BLOAD(a0, b0, kt + 4); }
;     __syncthreads();
;   }
.Lbr_gate_k:
	s_waitcnt vmcnt(8)
	s_barrier
	ds_read_b128 v[208:211], v240 offset:0
	ds_read_b128 v[224:227], v241 offset:0
	ds_read_b128 v[228:231], v241 offset:1024
	ds_read_b128 v[232:235], v241 offset:2048
	ds_read_b128 v[236:239], v241 offset:3072
	s_add_u32 m0, s52, 0xc000
	s_add_u32 s28, s28, 0x100000
	s_addc_u32 s29, s29, 0
	global_load_lds_dwordx4 v251, s[28:29]
	global_load_lds_dwordx4 v251, s[28:29] offset:1024
	s_add_u32 m0, s53, 0xc000
	s_add_u32 s30, s30, 0x30000
	s_addc_u32 s31, s31, 0
	global_load_lds_dwordx4 v251, s[30:31]
	global_load_lds_dwordx4 v251, s[30:31] offset:1024
	ds_read_b128 v[212:215], v240 offset:1024
	ds_read_b128 v[216:219], v240 offset:2048
	ds_read_b128 v[220:223], v240 offset:3072
	s_waitcnt lgkmcnt(6)
	v_mfma_f32_16x16x32_bf16 v[2:5], v[224:227], v[208:211], v[2:5]
	s_waitcnt lgkmcnt(5)
	v_mfma_f32_16x16x32_bf16 v[6:9], v[228:231], v[208:211], v[6:9]
	s_waitcnt lgkmcnt(4)
	v_mfma_f32_16x16x32_bf16 v[10:13], v[232:235], v[208:211], v[10:13]
	s_waitcnt lgkmcnt(3)
	v_mfma_f32_16x16x32_bf16 v[14:17], v[236:239], v[208:211], v[14:17]
	s_waitcnt lgkmcnt(2)
	v_mfma_f32_16x16x32_bf16 v[18:21], v[224:227], v[212:215], v[18:21]
	v_mfma_f32_16x16x32_bf16 v[22:25], v[228:231], v[212:215], v[22:25]
	v_mfma_f32_16x16x32_bf16 v[26:29], v[232:235], v[212:215], v[26:29]
	v_mfma_f32_16x16x32_bf16 v[30:33], v[236:239], v[212:215], v[30:33]
	s_waitcnt lgkmcnt(1)
	v_mfma_f32_16x16x32_bf16 v[34:37], v[224:227], v[216:219], v[34:37]
	v_mfma_f32_16x16x32_bf16 v[38:41], v[228:231], v[216:219], v[38:41]
	v_mfma_f32_16x16x32_bf16 v[42:45], v[232:235], v[216:219], v[42:45]
	v_mfma_f32_16x16x32_bf16 v[46:49], v[236:239], v[216:219], v[46:49]
	s_waitcnt lgkmcnt(0)
	v_mfma_f32_16x16x32_bf16 v[50:53], v[224:227], v[220:223], v[50:53]
	v_mfma_f32_16x16x32_bf16 v[54:57], v[228:231], v[220:223], v[54:57]
	v_mfma_f32_16x16x32_bf16 v[58:61], v[232:235], v[220:223], v[58:61]
	v_mfma_f32_16x16x32_bf16 v[62:65], v[236:239], v[220:223], v[62:65]
	s_waitcnt vmcnt(8)
	s_barrier
	ds_read_b128 v[208:211], v240 offset:16384
	ds_read_b128 v[224:227], v241 offset:16384
	ds_read_b128 v[228:231], v241 offset:17408
	ds_read_b128 v[232:235], v241 offset:18432
	ds_read_b128 v[236:239], v241 offset:19456
	s_add_u32 m0, s52, 0x0
	s_add_u32 s28, s28, 0x100000
	s_addc_u32 s29, s29, 0
	global_load_lds_dwordx4 v251, s[28:29]
	global_load_lds_dwordx4 v251, s[28:29] offset:1024
	s_add_u32 m0, s53, 0x0
	s_add_u32 s30, s30, 0x30000
	s_addc_u32 s31, s31, 0
	global_load_lds_dwordx4 v251, s[30:31]
	global_load_lds_dwordx4 v251, s[30:31] offset:1024
	ds_read_b128 v[212:215], v240 offset:17408
	ds_read_b128 v[216:219], v240 offset:18432
	ds_read_b128 v[220:223], v240 offset:19456
	s_waitcnt lgkmcnt(6)
	v_mfma_f32_16x16x32_bf16 v[2:5], v[224:227], v[208:211], v[2:5]
	s_waitcnt lgkmcnt(5)
	v_mfma_f32_16x16x32_bf16 v[6:9], v[228:231], v[208:211], v[6:9]
	s_waitcnt lgkmcnt(4)
	v_mfma_f32_16x16x32_bf16 v[10:13], v[232:235], v[208:211], v[10:13]
	s_waitcnt lgkmcnt(3)
	v_mfma_f32_16x16x32_bf16 v[14:17], v[236:239], v[208:211], v[14:17]
	s_waitcnt lgkmcnt(2)
	v_mfma_f32_16x16x32_bf16 v[18:21], v[224:227], v[212:215], v[18:21]
	v_mfma_f32_16x16x32_bf16 v[22:25], v[228:231], v[212:215], v[22:25]
	v_mfma_f32_16x16x32_bf16 v[26:29], v[232:235], v[212:215], v[26:29]
	v_mfma_f32_16x16x32_bf16 v[30:33], v[236:239], v[212:215], v[30:33]
	s_waitcnt lgkmcnt(1)
	v_mfma_f32_16x16x32_bf16 v[34:37], v[224:227], v[216:219], v[34:37]
	v_mfma_f32_16x16x32_bf16 v[38:41], v[228:231], v[216:219], v[38:41]
	v_mfma_f32_16x16x32_bf16 v[42:45], v[232:235], v[216:219], v[42:45]
	v_mfma_f32_16x16x32_bf16 v[46:49], v[236:239], v[216:219], v[46:49]
	s_waitcnt lgkmcnt(0)
	v_mfma_f32_16x16x32_bf16 v[50:53], v[224:227], v[220:223], v[50:53]
	v_mfma_f32_16x16x32_bf16 v[54:57], v[228:231], v[220:223], v[54:57]
	v_mfma_f32_16x16x32_bf16 v[58:61], v[232:235], v[220:223], v[58:61]
	v_mfma_f32_16x16x32_bf16 v[62:65], v[236:239], v[220:223], v[62:65]
	s_waitcnt vmcnt(8)
	s_barrier
	ds_read_b128 v[208:211], v240 offset:32768
	ds_read_b128 v[224:227], v241 offset:32768
	ds_read_b128 v[228:231], v241 offset:33792
	ds_read_b128 v[232:235], v241 offset:34816
	ds_read_b128 v[236:239], v241 offset:35840
	s_add_u32 m0, s52, 0x4000
	s_add_u32 s28, s28, 0x100000
	s_addc_u32 s29, s29, 0
	global_load_lds_dwordx4 v251, s[28:29]
	global_load_lds_dwordx4 v251, s[28:29] offset:1024
	s_add_u32 m0, s53, 0x4000
	s_add_u32 s30, s30, 0x30000
	s_addc_u32 s31, s31, 0
	global_load_lds_dwordx4 v251, s[30:31]
	global_load_lds_dwordx4 v251, s[30:31] offset:1024
	ds_read_b128 v[212:215], v240 offset:33792
	ds_read_b128 v[216:219], v240 offset:34816
	ds_read_b128 v[220:223], v240 offset:35840
	s_waitcnt lgkmcnt(6)
	v_mfma_f32_16x16x32_bf16 v[2:5], v[224:227], v[208:211], v[2:5]
	s_waitcnt lgkmcnt(5)
	v_mfma_f32_16x16x32_bf16 v[6:9], v[228:231], v[208:211], v[6:9]
	s_waitcnt lgkmcnt(4)
	v_mfma_f32_16x16x32_bf16 v[10:13], v[232:235], v[208:211], v[10:13]
	s_waitcnt lgkmcnt(3)
	v_mfma_f32_16x16x32_bf16 v[14:17], v[236:239], v[208:211], v[14:17]
	s_waitcnt lgkmcnt(2)
	v_mfma_f32_16x16x32_bf16 v[18:21], v[224:227], v[212:215], v[18:21]
	v_mfma_f32_16x16x32_bf16 v[22:25], v[228:231], v[212:215], v[22:25]
	v_mfma_f32_16x16x32_bf16 v[26:29], v[232:235], v[212:215], v[26:29]
	v_mfma_f32_16x16x32_bf16 v[30:33], v[236:239], v[212:215], v[30:33]
	s_waitcnt lgkmcnt(1)
	v_mfma_f32_16x16x32_bf16 v[34:37], v[224:227], v[216:219], v[34:37]
	v_mfma_f32_16x16x32_bf16 v[38:41], v[228:231], v[216:219], v[38:41]
	v_mfma_f32_16x16x32_bf16 v[42:45], v[232:235], v[216:219], v[42:45]
	v_mfma_f32_16x16x32_bf16 v[46:49], v[236:239], v[216:219], v[46:49]
	s_waitcnt lgkmcnt(0)
	v_mfma_f32_16x16x32_bf16 v[50:53], v[224:227], v[220:223], v[50:53]
	v_mfma_f32_16x16x32_bf16 v[54:57], v[228:231], v[220:223], v[54:57]
	v_mfma_f32_16x16x32_bf16 v[58:61], v[232:235], v[220:223], v[58:61]
	v_mfma_f32_16x16x32_bf16 v[62:65], v[236:239], v[220:223], v[62:65]
	s_waitcnt vmcnt(8)
	s_barrier
; #define BLOAD(A_, B_, kt) do { _Pragma("unroll") for (int i = 0; i < 4; ++i) { \
;     A_[i] = *(const u32x4*)((const char*)Ap + (aoff + (unsigned)(32 * i * lda + (kt) * 64) * 2u)); B_[i] = *(const u32x4*)((const char*)Wt + (woff + (unsigned)(32 * i * K + (kt) * 64) * 2u)); } } while (0)
; #define BLOAD(A_, B_, kt) do { _Pragma("unroll") for (int i = 0; i < 4; ++i) { \
;     A_[i] = *(const u32x4*)((const char*)Ap + (aoff + (unsigned)(32 * i * lda + (kt) * 64) * 2u)); B_[i] = *(const u32x4*)((const char*)Wt + (woff + (unsigned)(32 * i * K + (kt) * 64) * 2u)); } } while (0)
; #define BSTORE(A_, B_, buf) do { _Pragma("unroll") for (int i = 0; i < 4; ++i) { \
;     *(u32x4*)&As[(buf) * GBUF + (srow + 32 * i) * LDT + sc8] = A_[i]; \
;     *(u32x4*)&Bs[(buf) * GBUF + (srow + 32 * i) * LDT + sc8] = B_[i]; } } while (0)
; template <bool ROWNORM, int NK>
; DI void gemm_main_bf(const u16* __restrict__ Ap, int lda, const u16* __restrict__ Wt, f32x16 (&acc)[2][2], char* smem, float* rinv_s) {
;     ...
; #pragma unroll
;   for (int kt = 0; kt < nk; kt += 2) {
;     BCOMP(0);
;     BSTORE(a1, b1, 1);
;     if (kt + 3 < nk) BLOAD(a1, b1, kt + 3);
;     __syncthreads();
;     BCOMP(1);
;     if (kt + 2 < nk) { BSTORE(a0, b0, 0); if (kt + 4 < nk) BLOAD(a0, b0, kt + 4); }
;     __syncthreads();
;   }
	ds_read_b128 v[208:211], v240 offset:49152
	ds_read_b128 v[224:227], v241 offset:49152
	ds_read_b128 v[228:231], v241 offset:50176
	ds_read_b128 v[232:235], v241 offset:51200
	ds_read_b128 v[236:239], v241 offset:52224
	s_add_u32 m0, s52, 0x8000
	s_add_u32 s28, s28, 0x100000
	s_addc_u32 s29, s29, 0
	global_load_lds_dwordx4 v251, s[28:29]
	global_load_lds_dwordx4 v251, s[28:29] offset:1024
	s_add_u32 m0, s53, 0x8000
	s_add_u32 s30, s30, 0x30000
	s_addc_u32 s31, s31, 0
	global_load_lds_dwordx4 v251, s[30:31]
	global_load_lds_dwordx4 v251, s[30:31] offset:1024
	ds_read_b128 v[212:215], v240 offset:50176
	ds_read_b128 v[216:219], v240 offset:51200
	ds_read_b128 v[220:223], v240 offset:52224
	s_waitcnt lgkmcnt(6)
	v_mfma_f32_16x16x32_bf16 v[2:5], v[224:227], v[208:211], v[2:5]
	s_waitcnt lgkmcnt(5)
	v_mfma_f32_16x16x32_bf16 v[6:9], v[228:231], v[208:211], v[6:9]
	s_waitcnt lgkmcnt(4)
	v_mfma_f32_16x16x32_bf16 v[10:13], v[232:235], v[208:211], v[10:13]
	s_waitcnt lgkmcnt(3)
	v_mfma_f32_16x16x32_bf16 v[14:17], v[236:239], v[208:211], v[14:17]
	s_waitcnt lgkmcnt(2)
	v_mfma_f32_16x16x32_bf16 v[18:21], v[224:227], v[212:215], v[18:21]
	v_mfma_f32_16x16x32_bf16 v[22:25], v[228:231], v[212:215], v[22:25]
	v_mfma_f32_16x16x32_bf16 v[26:29], v[232:235], v[212:215], v[26:29]
	v_mfma_f32_16x16x32_bf16 v[30:33], v[236:239], v[212:215], v[30:33]
	s_waitcnt lgkmcnt(1)
	v_mfma_f32_16x16x32_bf16 v[34:37], v[224:227], v[216:219], v[34:37]
	v_mfma_f32_16x16x32_bf16 v[38:41], v[228:231], v[216:219], v[38:41]
	v_mfma_f32_16x16x32_bf16 v[42:45], v[232:235], v[216:219], v[42:45]
	v_mfma_f32_16x16x32_bf16 v[46:49], v[236:239], v[216:219], v[46:49]
	s_waitcnt lgkmcnt(0)
	v_mfma_f32_16x16x32_bf16 v[50:53], v[224:227], v[220:223], v[50:53]
	v_mfma_f32_16x16x32_bf16 v[54:57], v[228:231], v[220:223], v[54:57]
	v_mfma_f32_16x16x32_bf16 v[58:61], v[232:235], v[220:223], v[58:61]
	v_mfma_f32_16x16x32_bf16 v[62:65], v[236:239], v[220:223], v[62:65]
	s_sub_u32 s74, s74, 1
	s_cmp_lg_u32 s74, 0
	s_cbranch_scc1 .Lbr_gate_k
	s_waitcnt vmcnt(8)
	s_barrier
	ds_read_b128 v[208:211], v240 offset:0
	ds_read_b128 v[224:227], v241 offset:0
	ds_read_b128 v[228:231], v241 offset:1024
	ds_read_b128 v[232:235], v241 offset:2048
	ds_read_b128 v[236:239], v241 offset:3072
	s_add_u32 m0, s52, 0xc000
	s_add_u32 s28, s28, 0x100000
	s_addc_u32 s29, s29, 0
	global_load_lds_dwordx4 v251, s[28:29]
	global_load_lds_dwordx4 v251, s[28:29] offset:1024
	s_add_u32 m0, s53, 0xc000
	s_add_u32 s30, s30, 0x30000
	s_addc_u32 s31, s31, 0
	global_load_lds_dwordx4 v251, s[30:31]
	global_load_lds_dwordx4 v251, s[30:31] offset:1024
	ds_read_b128 v[212:215], v240 offset:1024
	ds_read_b128 v[216:219], v240 offset:2048
	ds_read_b128 v[220:223], v240 offset:3072
	s_waitcnt lgkmcnt(6)
	v_mfma_f32_16x16x32_bf16 v[2:5], v[224:227], v[208:211], v[2:5]
	s_waitcnt lgkmcnt(5)
	v_mfma_f32_16x16x32_bf16 v[6:9], v[228:231], v[208:211], v[6:9]
	s_waitcnt lgkmcnt(4)
	v_mfma_f32_16x16x32_bf16 v[10:13], v[232:235], v[208:211], v[10:13]
	s_waitcnt lgkmcnt(3)
	v_mfma_f32_16x16x32_bf16 v[14:17], v[236:239], v[208:211], v[14:17]
	s_waitcnt lgkmcnt(2)
	v_mfma_f32_16x16x32_bf16 v[18:21], v[224:227], v[212:215], v[18:21]
	v_mfma_f32_16x16x32_bf16 v[22:25], v[228:231], v[212:215], v[22:25]
	v_mfma_f32_16x16x32_bf16 v[26:29], v[232:235], v[212:215], v[26:29]
	v_mfma_f32_16x16x32_bf16 v[30:33], v[236:239], v[212:215], v[30:33]
	s_waitcnt lgkmcnt(1)
	v_mfma_f32_16x16x32_bf16 v[34:37], v[224:227], v[216:219], v[34:37]
	v_mfma_f32_16x16x32_bf16 v[38:41], v[228:231], v[216:219], v[38:41]
	v_mfma_f32_16x16x32_bf16 v[42:45], v[232:235], v[216:219], v[42:45]
	v_mfma_f32_16x16x32_bf16 v[46:49], v[236:239], v[216:219], v[46:49]
	s_waitcnt lgkmcnt(0)
	v_mfma_f32_16x16x32_bf16 v[50:53], v[224:227], v[220:223], v[50:53]
	v_mfma_f32_16x16x32_bf16 v[54:57], v[228:231], v[220:223], v[54:57]
	v_mfma_f32_16x16x32_bf16 v[58:61], v[232:235], v[220:223], v[58:61]
	v_mfma_f32_16x16x32_bf16 v[62:65], v[236:239], v[220:223], v[62:65]
	s_waitcnt vmcnt(8)
	s_barrier
	ds_read_b128 v[208:211], v240 offset:16384
	ds_read_b128 v[224:227], v241 offset:16384
	ds_read_b128 v[228:231], v241 offset:17408
	ds_read_b128 v[232:235], v241 offset:18432
	ds_read_b128 v[236:239], v241 offset:19456
	ds_read_b128 v[212:215], v240 offset:17408
	ds_read_b128 v[216:219], v240 offset:18432
	ds_read_b128 v[220:223], v240 offset:19456
	s_waitcnt lgkmcnt(6)
	v_mfma_f32_16x16x32_bf16 v[2:5], v[224:227], v[208:211], v[2:5]
	s_waitcnt lgkmcnt(5)
	v_mfma_f32_16x16x32_bf16 v[6:9], v[228:231], v[208:211], v[6:9]
	s_waitcnt lgkmcnt(4)
	v_mfma_f32_16x16x32_bf16 v[10:13], v[232:235], v[208:211], v[10:13]
	s_waitcnt lgkmcnt(3)
	v_mfma_f32_16x16x32_bf16 v[14:17], v[236:239], v[208:211], v[14:17]
	s_waitcnt lgkmcnt(2)
	v_mfma_f32_16x16x32_bf16 v[18:21], v[224:227], v[212:215], v[18:21]
	v_mfma_f32_16x16x32_bf16 v[22:25], v[228:231], v[212:215], v[22:25]
	v_mfma_f32_16x16x32_bf16 v[26:29], v[232:235], v[212:215], v[26:29]
	v_mfma_f32_16x16x32_bf16 v[30:33], v[236:239], v[212:215], v[30:33]
	s_waitcnt lgkmcnt(1)
	v_mfma_f32_16x16x32_bf16 v[34:37], v[224:227], v[216:219], v[34:37]
	v_mfma_f32_16x16x32_bf16 v[38:41], v[228:231], v[216:219], v[38:41]
	v_mfma_f32_16x16x32_bf16 v[42:45], v[232:235], v[216:219], v[42:45]
	v_mfma_f32_16x16x32_bf16 v[46:49], v[236:239], v[216:219], v[46:49]
	s_waitcnt lgkmcnt(0)
	v_mfma_f32_16x16x32_bf16 v[50:53], v[224:227], v[220:223], v[50:53]
	v_mfma_f32_16x16x32_bf16 v[54:57], v[228:231], v[220:223], v[54:57]
	v_mfma_f32_16x16x32_bf16 v[58:61], v[232:235], v[220:223], v[58:61]
	v_mfma_f32_16x16x32_bf16 v[62:65], v[236:239], v[220:223], v[62:65]
	s_waitcnt vmcnt(4)
	s_barrier
; DI unsigned pk2(float a, float b) { f2_t v = {a, b}; bf2_t r = __builtin_convertvector(v, bf2_t); return __builtin_bit_cast(unsigned, r); }
; DI void tile_branch(const Params& p, int l, int tile, char* smem) {
;     ...
;       __syncthreads();
; #pragma unroll
;       for (int mt = 0; mt < 2; ++mt)
; #pragma unroll
;         for (int g4 = 0; g4 < 4; ++g4) {
;           const f32x4 r4 = *(const f32x4*)&rinv_s[wm * 64 + mt * 32 + 8 * g4 + 4 * hi];
; #pragma unroll
;           for (int nt = 0; nt < 2; ++nt) {
;             const float s0 = 1.f / (1.f + __expf(-accg[mt][nt][4 * g4 + 0] * r4[0])), s1 = 1.f / (1.f + __expf(-accg[mt][nt][4 * g4 + 1] * r4[1]));
;             const float s2 = 1.f / (1.f + __expf(-accg[mt][nt][4 * g4 + 2] * r4[2])), s3 = 1.f / (1.f + __expf(-accg[mt][nt][4 * g4 + 3] * r4[3]));
;             gpk[mt][nt][2 * g4] = pk2(s0, s1); gpk[mt][nt][2 * g4 + 1] = pk2(s2, s3);
;           }
;         }
	ds_read_b128 v[208:211], v240 offset:32768
	ds_read_b128 v[224:227], v241 offset:32768
	ds_read_b128 v[228:231], v241 offset:33792
	ds_read_b128 v[232:235], v241 offset:34816
	ds_read_b128 v[236:239], v241 offset:35840
	ds_read_b128 v[212:215], v240 offset:33792
	ds_read_b128 v[216:219], v240 offset:34816
	ds_read_b128 v[220:223], v240 offset:35840
	s_waitcnt lgkmcnt(6)
	v_mfma_f32_16x16x32_bf16 v[2:5], v[224:227], v[208:211], v[2:5]
	s_waitcnt lgkmcnt(5)
	v_mfma_f32_16x16x32_bf16 v[6:9], v[228:231], v[208:211], v[6:9]
	s_waitcnt lgkmcnt(4)
	v_mfma_f32_16x16x32_bf16 v[10:13], v[232:235], v[208:211], v[10:13]
	s_waitcnt lgkmcnt(3)
	v_mfma_f32_16x16x32_bf16 v[14:17], v[236:239], v[208:211], v[14:17]
	s_waitcnt lgkmcnt(2)
	v_mfma_f32_16x16x32_bf16 v[18:21], v[224:227], v[212:215], v[18:21]
	v_mfma_f32_16x16x32_bf16 v[22:25], v[228:231], v[212:215], v[22:25]
	v_mfma_f32_16x16x32_bf16 v[26:29], v[232:235], v[212:215], v[26:29]
	v_mfma_f32_16x16x32_bf16 v[30:33], v[236:239], v[212:215], v[30:33]
	s_waitcnt lgkmcnt(1)
	v_mfma_f32_16x16x32_bf16 v[34:37], v[224:227], v[216:219], v[34:37]
	v_mfma_f32_16x16x32_bf16 v[38:41], v[228:231], v[216:219], v[38:41]
	v_mfma_f32_16x16x32_bf16 v[42:45], v[232:235], v[216:219], v[42:45]
	v_mfma_f32_16x16x32_bf16 v[46:49], v[236:239], v[216:219], v[46:49]
	s_waitcnt lgkmcnt(0)
	v_mfma_f32_16x16x32_bf16 v[50:53], v[224:227], v[220:223], v[50:53]
	v_mfma_f32_16x16x32_bf16 v[54:57], v[228:231], v[220:223], v[54:57]
	v_mfma_f32_16x16x32_bf16 v[58:61], v[232:235], v[220:223], v[58:61]
	v_mfma_f32_16x16x32_bf16 v[62:65], v[236:239], v[220:223], v[62:65]
	s_waitcnt vmcnt(0)
	s_barrier
	ds_read_b128 v[208:211], v240 offset:49152
	ds_read_b128 v[224:227], v241 offset:49152
	ds_read_b128 v[228:231], v241 offset:50176
	ds_read_b128 v[232:235], v241 offset:51200
	ds_read_b128 v[236:239], v241 offset:52224
	ds_read_b128 v[212:215], v240 offset:50176
	ds_read_b128 v[216:219], v240 offset:51200
	ds_read_b128 v[220:223], v240 offset:52224
	s_waitcnt lgkmcnt(6)
	v_mfma_f32_16x16x32_bf16 v[2:5], v[224:227], v[208:211], v[2:5]
	s_waitcnt lgkmcnt(5)
	v_mfma_f32_16x16x32_bf16 v[6:9], v[228:231], v[208:211], v[6:9]
	s_waitcnt lgkmcnt(4)
	v_mfma_f32_16x16x32_bf16 v[10:13], v[232:235], v[208:211], v[10:13]
	s_waitcnt lgkmcnt(3)
	v_mfma_f32_16x16x32_bf16 v[14:17], v[236:239], v[208:211], v[14:17]
	s_waitcnt lgkmcnt(2)
	v_mfma_f32_16x16x32_bf16 v[18:21], v[224:227], v[212:215], v[18:21]
	v_mfma_f32_16x16x32_bf16 v[22:25], v[228:231], v[212:215], v[22:25]
	v_mfma_f32_16x16x32_bf16 v[26:29], v[232:235], v[212:215], v[26:29]
	v_mfma_f32_16x16x32_bf16 v[30:33], v[236:239], v[212:215], v[30:33]
	s_waitcnt lgkmcnt(1)
	v_mfma_f32_16x16x32_bf16 v[34:37], v[224:227], v[216:219], v[34:37]
	v_mfma_f32_16x16x32_bf16 v[38:41], v[228:231], v[216:219], v[38:41]
	v_mfma_f32_16x16x32_bf16 v[42:45], v[232:235], v[216:219], v[42:45]
	v_mfma_f32_16x16x32_bf16 v[46:49], v[236:239], v[216:219], v[46:49]
	s_waitcnt lgkmcnt(0)
	v_mfma_f32_16x16x32_bf16 v[50:53], v[224:227], v[220:223], v[50:53]
	v_mfma_f32_16x16x32_bf16 v[54:57], v[228:231], v[220:223], v[54:57]
	v_mfma_f32_16x16x32_bf16 v[58:61], v[232:235], v[220:223], v[58:61]
	v_mfma_f32_16x16x32_bf16 v[62:65], v[236:239], v[220:223], v[62:65]
	s_mov_b64 s[28:29], s[48:49]
	s_mov_b64 s[30:31], s[50:51]
	ds_read_b32 v162, v250 offset:0
	ds_read_b32 v163, v250 offset:64
	ds_read_b32 v164, v250 offset:128
	ds_read_b32 v165, v250 offset:192
	s_waitcnt lgkmcnt(0)
	v_mul_f32_e32 v162, 0xbfb8aa3b, v162
	v_mul_f32_e32 v163, 0xbfb8aa3b, v163
	v_mul_f32_e32 v164, 0xbfb8aa3b, v164
	v_mul_f32_e32 v165, 0xbfb8aa3b, v165
	v_mul_f32_e32 v166, v162, v2
	v_mul_f32_e32 v167, v162, v3
	v_mul_f32_e32 v168, v162, v4
	v_mul_f32_e32 v169, v162, v5
	v_exp_f32_e32 v166, v166
	v_exp_f32_e32 v167, v167
	v_exp_f32_e32 v168, v168
	v_exp_f32_e32 v169, v169
	v_add_f32_e32 v166, 1.0, v166
	v_add_f32_e32 v167, 1.0, v167
	v_add_f32_e32 v168, 1.0, v168
	v_add_f32_e32 v169, 1.0, v169
	v_rcp_f32_e32 v166, v166
	v_rcp_f32_e32 v167, v167
	v_rcp_f32_e32 v168, v168
	v_rcp_f32_e32 v169, v169
	v_cvt_pk_bf16_f32 v130, v166, v167
	v_cvt_pk_bf16_f32 v131, v168, v169
	v_mul_f32_e32 v166, v162, v6
	v_mul_f32_e32 v167, v162, v7
	v_mul_f32_e32 v168, v162, v8
	v_mul_f32_e32 v169, v162, v9
	v_exp_f32_e32 v166, v166
	v_exp_f32_e32 v167, v167
	v_exp_f32_e32 v168, v168
	v_exp_f32_e32 v169, v169
	v_add_f32_e32 v166, 1.0, v166
	v_add_f32_e32 v167, 1.0, v167
	v_add_f32_e32 v168, 1.0, v168
	v_add_f32_e32 v169, 1.0, v169
	v_rcp_f32_e32 v166, v166
	v_rcp_f32_e32 v167, v167
	v_rcp_f32_e32 v168, v168
	v_rcp_f32_e32 v169, v169
	v_cvt_pk_bf16_f32 v132, v166, v167
	v_cvt_pk_bf16_f32 v133, v168, v169
	v_mul_f32_e32 v166, v162, v10
	v_mul_f32_e32 v167, v162, v11
	v_mul_f32_e32 v168, v162, v12
	v_mul_f32_e32 v169, v162, v13
	v_exp_f32_e32 v166, v166
	v_exp_f32_e32 v167, v167
	v_exp_f32_e32 v168, v168
	v_exp_f32_e32 v169, v169
	v_add_f32_e32 v166, 1.0, v166
	v_add_f32_e32 v167, 1.0, v167
	v_add_f32_e32 v168, 1.0, v168
	v_add_f32_e32 v169, 1.0, v169
	v_rcp_f32_e32 v166, v166
	v_rcp_f32_e32 v167, v167
	v_rcp_f32_e32 v168, v168
	v_rcp_f32_e32 v169, v169
	v_cvt_pk_bf16_f32 v134, v166, v167
	v_cvt_pk_bf16_f32 v135, v168, v169
	v_mul_f32_e32 v166, v162, v14
	v_mul_f32_e32 v167, v162, v15
	v_mul_f32_e32 v168, v162, v16
	v_mul_f32_e32 v169, v162, v17
	v_exp_f32_e32 v166, v166
	v_exp_f32_e32 v167, v167
	v_exp_f32_e32 v168, v168
	v_exp_f32_e32 v169, v169
	v_add_f32_e32 v166, 1.0, v166
	v_add_f32_e32 v167, 1.0, v167
	v_add_f32_e32 v168, 1.0, v168
	v_add_f32_e32 v169, 1.0, v169
	v_rcp_f32_e32 v166, v166
	v_rcp_f32_e32 v167, v167
	v_rcp_f32_e32 v168, v168
	v_rcp_f32_e32 v169, v169
; DI unsigned pk2(float a, float b) { f2_t v = {a, b}; bf2_t r = __builtin_convertvector(v, bf2_t); return __builtin_bit_cast(unsigned, r); }
; DI void tile_branch(const Params& p, int l, int tile, char* smem) {
;     ...
;         for (int g4 = 0; g4 < 4; ++g4) {
;           const f32x4 r4 = *(const f32x4*)&rinv_s[wm * 64 + mt * 32 + 8 * g4 + 4 * hi];
; #pragma unroll
;           for (int nt = 0; nt < 2; ++nt) {
;             const float s0 = 1.f / (1.f + __expf(-accg[mt][nt][4 * g4 + 0] * r4[0])), s1 = 1.f / (1.f + __expf(-accg[mt][nt][4 * g4 + 1] * r4[1]));
;             const float s2 = 1.f / (1.f + __expf(-accg[mt][nt][4 * g4 + 2] * r4[2])), s3 = 1.f / (1.f + __expf(-accg[mt][nt][4 * g4 + 3] * r4[3]));
;             gpk[mt][nt][2 * g4] = pk2(s0, s1); gpk[mt][nt][2 * g4 + 1] = pk2(s2, s3);
;           }
;         }
	v_cvt_pk_bf16_f32 v136, v166, v167
	v_cvt_pk_bf16_f32 v137, v168, v169
	v_mul_f32_e32 v166, v163, v18
	v_mul_f32_e32 v167, v163, v19
	v_mul_f32_e32 v168, v163, v20
	v_mul_f32_e32 v169, v163, v21
	v_exp_f32_e32 v166, v166
	v_exp_f32_e32 v167, v167
	v_exp_f32_e32 v168, v168
	v_exp_f32_e32 v169, v169
	v_add_f32_e32 v166, 1.0, v166
	v_add_f32_e32 v167, 1.0, v167
	v_add_f32_e32 v168, 1.0, v168
	v_add_f32_e32 v169, 1.0, v169
	v_rcp_f32_e32 v166, v166
	v_rcp_f32_e32 v167, v167
	v_rcp_f32_e32 v168, v168
	v_rcp_f32_e32 v169, v169
	v_cvt_pk_bf16_f32 v138, v166, v167
	v_cvt_pk_bf16_f32 v139, v168, v169
	v_mul_f32_e32 v166, v163, v22
	v_mul_f32_e32 v167, v163, v23
	v_mul_f32_e32 v168, v163, v24
	v_mul_f32_e32 v169, v163, v25
	v_exp_f32_e32 v166, v166
	v_exp_f32_e32 v167, v167
	v_exp_f32_e32 v168, v168
	v_exp_f32_e32 v169, v169
	v_add_f32_e32 v166, 1.0, v166
	v_add_f32_e32 v167, 1.0, v167
	v_add_f32_e32 v168, 1.0, v168
	v_add_f32_e32 v169, 1.0, v169
	v_rcp_f32_e32 v166, v166
	v_rcp_f32_e32 v167, v167
	v_rcp_f32_e32 v168, v168
	v_rcp_f32_e32 v169, v169
	v_cvt_pk_bf16_f32 v140, v166, v167
	v_cvt_pk_bf16_f32 v141, v168, v169
	v_mul_f32_e32 v166, v163, v26
	v_mul_f32_e32 v167, v163, v27
	v_mul_f32_e32 v168, v163, v28
	v_mul_f32_e32 v169, v163, v29
	v_exp_f32_e32 v166, v166
	v_exp_f32_e32 v167, v167
	v_exp_f32_e32 v168, v168
	v_exp_f32_e32 v169, v169
	v_add_f32_e32 v166, 1.0, v166
	v_add_f32_e32 v167, 1.0, v167
	v_add_f32_e32 v168, 1.0, v168
	v_add_f32_e32 v169, 1.0, v169
	v_rcp_f32_e32 v166, v166
	v_rcp_f32_e32 v167, v167
	v_rcp_f32_e32 v168, v168
	v_rcp_f32_e32 v169, v169
	v_cvt_pk_bf16_f32 v142, v166, v167
	v_cvt_pk_bf16_f32 v143, v168, v169
	v_mul_f32_e32 v166, v163, v30
	v_mul_f32_e32 v167, v163, v31
	v_mul_f32_e32 v168, v163, v32
	v_mul_f32_e32 v169, v163, v33
	v_exp_f32_e32 v166, v166
	v_exp_f32_e32 v167, v167
	v_exp_f32_e32 v168, v168
	v_exp_f32_e32 v169, v169
	v_add_f32_e32 v166, 1.0, v166
	v_add_f32_e32 v167, 1.0, v167
	v_add_f32_e32 v168, 1.0, v168
	v_add_f32_e32 v169, 1.0, v169
	v_rcp_f32_e32 v166, v166
	v_rcp_f32_e32 v167, v167
	v_rcp_f32_e32 v168, v168
	v_rcp_f32_e32 v169, v169
	v_cvt_pk_bf16_f32 v144, v166, v167
	v_cvt_pk_bf16_f32 v145, v168, v169
	v_mul_f32_e32 v166, v164, v34
	v_mul_f32_e32 v167, v164, v35
	v_mul_f32_e32 v168, v164, v36
	v_mul_f32_e32 v169, v164, v37
	v_exp_f32_e32 v166, v166
	v_exp_f32_e32 v167, v167
	v_exp_f32_e32 v168, v168
	v_exp_f32_e32 v169, v169
	v_add_f32_e32 v166, 1.0, v166
	v_add_f32_e32 v167, 1.0, v167
	v_add_f32_e32 v168, 1.0, v168
	v_add_f32_e32 v169, 1.0, v169
	v_rcp_f32_e32 v166, v166
	v_rcp_f32_e32 v167, v167
	v_rcp_f32_e32 v168, v168
	v_rcp_f32_e32 v169, v169
	v_cvt_pk_bf16_f32 v146, v166, v167
	v_cvt_pk_bf16_f32 v147, v168, v169
	v_mul_f32_e32 v166, v164, v38
	v_mul_f32_e32 v167, v164, v39
	v_mul_f32_e32 v168, v164, v40
	v_mul_f32_e32 v169, v164, v41
	v_exp_f32_e32 v166, v166
	v_exp_f32_e32 v167, v167
	v_exp_f32_e32 v168, v168
	v_exp_f32_e32 v169, v169
	v_add_f32_e32 v166, 1.0, v166
	v_add_f32_e32 v167, 1.0, v167
	v_add_f32_e32 v168, 1.0, v168
	v_add_f32_e32 v169, 1.0, v169
	v_rcp_f32_e32 v166, v166
	v_rcp_f32_e32 v167, v167
	v_rcp_f32_e32 v168, v168
	v_rcp_f32_e32 v169, v169
	v_cvt_pk_bf16_f32 v148, v166, v167
	v_cvt_pk_bf16_f32 v149, v168, v169
	v_mul_f32_e32 v166, v164, v42
	v_mul_f32_e32 v167, v164, v43
	v_mul_f32_e32 v168, v164, v44
	v_mul_f32_e32 v169, v164, v45
	v_exp_f32_e32 v166, v166
	v_exp_f32_e32 v167, v167
	v_exp_f32_e32 v168, v168
	v_exp_f32_e32 v169, v169
	v_add_f32_e32 v166, 1.0, v166
	v_add_f32_e32 v167, 1.0, v167
	v_add_f32_e32 v168, 1.0, v168
	v_add_f32_e32 v169, 1.0, v169
	v_rcp_f32_e32 v166, v166
	v_rcp_f32_e32 v167, v167
	v_rcp_f32_e32 v168, v168
	v_rcp_f32_e32 v169, v169
	v_cvt_pk_bf16_f32 v150, v166, v167
	v_cvt_pk_bf16_f32 v151, v168, v169
	v_mul_f32_e32 v166, v164, v46
	v_mul_f32_e32 v167, v164, v47
	v_mul_f32_e32 v168, v164, v48
	v_mul_f32_e32 v169, v164, v49
	v_exp_f32_e32 v166, v166
	v_exp_f32_e32 v167, v167
	v_exp_f32_e32 v168, v168
	v_exp_f32_e32 v169, v169
	v_add_f32_e32 v166, 1.0, v166
	v_add_f32_e32 v167, 1.0, v167
	v_add_f32_e32 v168, 1.0, v168
	v_add_f32_e32 v169, 1.0, v169
	v_rcp_f32_e32 v166, v166
	v_rcp_f32_e32 v167, v167
	v_rcp_f32_e32 v168, v168
	v_rcp_f32_e32 v169, v169
	v_cvt_pk_bf16_f32 v152, v166, v167
	v_cvt_pk_bf16_f32 v153, v168, v169
	v_mul_f32_e32 v166, v165, v50
	v_mul_f32_e32 v167, v165, v51
	v_mul_f32_e32 v168, v165, v52
	v_mul_f32_e32 v169, v165, v53
	v_exp_f32_e32 v166, v166
	v_exp_f32_e32 v167, v167
	v_exp_f32_e32 v168, v168
	v_exp_f32_e32 v169, v169
	v_add_f32_e32 v166, 1.0, v166
	v_add_f32_e32 v167, 1.0, v167
	v_add_f32_e32 v168, 1.0, v168
	v_add_f32_e32 v169, 1.0, v169
	v_rcp_f32_e32 v166, v166
	v_rcp_f32_e32 v167, v167
	v_rcp_f32_e32 v168, v168
	v_rcp_f32_e32 v169, v169
	v_cvt_pk_bf16_f32 v154, v166, v167
	v_cvt_pk_bf16_f32 v155, v168, v169
	v_mul_f32_e32 v166, v165, v54
	v_mul_f32_e32 v167, v165, v55
	v_mul_f32_e32 v168, v165, v56
	v_mul_f32_e32 v169, v165, v57
	v_exp_f32_e32 v166, v166
	v_exp_f32_e32 v167, v167
	v_exp_f32_e32 v168, v168
	v_exp_f32_e32 v169, v169
	v_add_f32_e32 v166, 1.0, v166
	v_add_f32_e32 v167, 1.0, v167
	v_add_f32_e32 v168, 1.0, v168
	v_add_f32_e32 v169, 1.0, v169
	v_rcp_f32_e32 v166, v166
	v_rcp_f32_e32 v167, v167
	v_rcp_f32_e32 v168, v168
	v_rcp_f32_e32 v169, v169
	v_cvt_pk_bf16_f32 v156, v166, v167
	v_cvt_pk_bf16_f32 v157, v168, v169
	v_mul_f32_e32 v166, v165, v58
	v_mul_f32_e32 v167, v165, v59
	v_mul_f32_e32 v168, v165, v60
	v_mul_f32_e32 v169, v165, v61
	v_exp_f32_e32 v166, v166
	v_exp_f32_e32 v167, v167
	v_exp_f32_e32 v168, v168
	v_exp_f32_e32 v169, v169
	v_add_f32_e32 v166, 1.0, v166
	v_add_f32_e32 v167, 1.0, v167
; DI unsigned pk2(float a, float b) { f2_t v = {a, b}; bf2_t r = __builtin_convertvector(v, bf2_t); return __builtin_bit_cast(unsigned, r); }
; #define BLOAD(A_, B_, kt) do { _Pragma("unroll") for (int i = 0; i < 4; ++i) { \
;     A_[i] = *(const u32x4*)((const char*)Ap + (aoff + (unsigned)(32 * i * lda + (kt) * 64) * 2u)); B_[i] = *(const u32x4*)((const char*)Wt + (woff + (unsigned)(32 * i * K + (kt) * 64) * 2u)); } } while (0)
; #define BLOAD(A_, B_, kt) do { _Pragma("unroll") for (int i = 0; i < 4; ++i) { \
;     A_[i] = *(const u32x4*)((const char*)Ap + (aoff + (unsigned)(32 * i * lda + (kt) * 64) * 2u)); B_[i] = *(const u32x4*)((const char*)Wt + (woff + (unsigned)(32 * i * K + (kt) * 64) * 2u)); } } while (0)
; #define BSTORE(A_, B_, buf) do { _Pragma("unroll") for (int i = 0; i < 4; ++i) { \
;     *(u32x4*)&As[(buf) * GBUF + (srow + 32 * i) * LDT + sc8] = A_[i]; \
;     *(u32x4*)&Bs[(buf) * GBUF + (srow + 32 * i) * LDT + sc8] = B_[i]; } } while (0)
; template <bool ROWNORM, int NK>
; DI void gemm_main_bf(const u16* __restrict__ Ap, int lda, const u16* __restrict__ Wt, f32x16 (&acc)[2][2], char* smem, float* rinv_s) {
;     ...
;   __builtin_amdgcn_s_setprio(0);
;   BLOAD(a0, b0, 0); BLOAD(a1, b1, 1);
;   __syncthreads();
;   BSTORE(a0, b0, 0);
;   BLOAD(a0, b0, 2);
;   __syncthreads();
; DI void tile_branch(const Params& p, int l, int tile, char* smem) {
;     ...
;             const float s0 = 1.f / (1.f + __expf(-accg[mt][nt][4 * g4 + 0] * r4[0])), s1 = 1.f / (1.f + __expf(-accg[mt][nt][4 * g4 + 1] * r4[1]));
;             const float s2 = 1.f / (1.f + __expf(-accg[mt][nt][4 * g4 + 2] * r4[2])), s3 = 1.f / (1.f + __expf(-accg[mt][nt][4 * g4 + 3] * r4[3]));
;             gpk[mt][nt][2 * g4] = pk2(s0, s1); gpk[mt][nt][2 * g4 + 1] = pk2(s2, s3);
;           }
;         }
;     }
;     f32x16 acc[2][2]; zero_acc(acc);
;     gemm_main_bf<false, 8>((const u16*)(p.ws + OFF_BR) + (size_t)(br * CT + m0) * 512, 512,
;                             (const u16*)(p.ws + OFF_WBR + (l * 3 + br) * SZ_WBR) + (size_t)n0 * 512, acc, smem, nullptr);
	v_add_f32_e32 v168, 1.0, v168
	v_add_f32_e32 v169, 1.0, v169
	v_rcp_f32_e32 v166, v166
	v_rcp_f32_e32 v167, v167
	v_rcp_f32_e32 v168, v168
	v_rcp_f32_e32 v169, v169
	v_cvt_pk_bf16_f32 v158, v166, v167
	v_cvt_pk_bf16_f32 v159, v168, v169
	v_mul_f32_e32 v166, v165, v62
	v_mul_f32_e32 v167, v165, v63
	v_mul_f32_e32 v168, v165, v64
	v_mul_f32_e32 v169, v165, v65
	v_exp_f32_e32 v166, v166
	v_exp_f32_e32 v167, v167
	v_exp_f32_e32 v168, v168
	v_exp_f32_e32 v169, v169
	v_add_f32_e32 v166, 1.0, v166
	v_add_f32_e32 v167, 1.0, v167
	v_add_f32_e32 v168, 1.0, v168
	v_add_f32_e32 v169, 1.0, v169
	v_rcp_f32_e32 v166, v166
	v_rcp_f32_e32 v167, v167
	v_rcp_f32_e32 v168, v168
	v_rcp_f32_e32 v169, v169
	v_cvt_pk_bf16_f32 v160, v166, v167
	v_cvt_pk_bf16_f32 v161, v168, v169
	s_add_u32 m0, s52, 0x0
	s_nop 0
	global_load_lds_dwordx4 v244, s[28:29]
	global_load_lds_dwordx4 v245, s[28:29] offset:1024
	s_add_u32 m0, s53, 0x0
	s_nop 0
	global_load_lds_dwordx4 v251, s[30:31]
	global_load_lds_dwordx4 v251, s[30:31] offset:1024
	s_add_u32 m0, s52, 0x4000
	s_add_u32 s28, s28, 0x40
	s_addc_u32 s29, s29, 0
	global_load_lds_dwordx4 v244, s[28:29]
	global_load_lds_dwordx4 v245, s[28:29] offset:1024
	s_add_u32 m0, s53, 0x4000
	s_add_u32 s30, s30, 0x10000
	s_addc_u32 s31, s31, 0
	global_load_lds_dwordx4 v251, s[30:31]
	global_load_lds_dwordx4 v251, s[30:31] offset:1024
	s_add_u32 m0, s52, 0x8000
	s_add_u32 s28, s28, 0x40
	s_addc_u32 s29, s29, 0
	global_load_lds_dwordx4 v244, s[28:29]
	global_load_lds_dwordx4 v245, s[28:29] offset:1024
	s_add_u32 m0, s53, 0x8000
	s_add_u32 s30, s30, 0x10000
	s_addc_u32 s31, s31, 0
	global_load_lds_dwordx4 v251, s[30:31]
	global_load_lds_dwordx4 v251, s[30:31] offset:1024
	v_mov_b32_e32 v2, 0
	v_mov_b32_e32 v3, 0
	v_mov_b32_e32 v4, 0
	v_mov_b32_e32 v5, 0
	v_mov_b32_e32 v6, 0
	v_mov_b32_e32 v7, 0
	v_mov_b32_e32 v8, 0
	v_mov_b32_e32 v9, 0
	v_mov_b32_e32 v10, 0
	v_mov_b32_e32 v11, 0
	v_mov_b32_e32 v12, 0
	v_mov_b32_e32 v13, 0
	v_mov_b32_e32 v14, 0
	v_mov_b32_e32 v15, 0
	v_mov_b32_e32 v16, 0
	v_mov_b32_e32 v17, 0
	v_mov_b32_e32 v18, 0
	v_mov_b32_e32 v19, 0
	v_mov_b32_e32 v20, 0
	v_mov_b32_e32 v21, 0
	v_mov_b32_e32 v22, 0
	v_mov_b32_e32 v23, 0
	v_mov_b32_e32 v24, 0
	v_mov_b32_e32 v25, 0
	v_mov_b32_e32 v26, 0
	v_mov_b32_e32 v27, 0
	v_mov_b32_e32 v28, 0
	v_mov_b32_e32 v29, 0
	v_mov_b32_e32 v30, 0
	v_mov_b32_e32 v31, 0
	v_mov_b32_e32 v32, 0
	v_mov_b32_e32 v33, 0
	v_mov_b32_e32 v34, 0
	v_mov_b32_e32 v35, 0
	v_mov_b32_e32 v36, 0
	v_mov_b32_e32 v37, 0
	v_mov_b32_e32 v38, 0
	v_mov_b32_e32 v39, 0
	v_mov_b32_e32 v40, 0
	v_mov_b32_e32 v41, 0
	v_mov_b32_e32 v42, 0
	v_mov_b32_e32 v43, 0
	v_mov_b32_e32 v44, 0
	v_mov_b32_e32 v45, 0
	v_mov_b32_e32 v46, 0
	v_mov_b32_e32 v47, 0
	v_mov_b32_e32 v48, 0
	v_mov_b32_e32 v49, 0
	v_mov_b32_e32 v50, 0
	v_mov_b32_e32 v51, 0
	v_mov_b32_e32 v52, 0
	v_mov_b32_e32 v53, 0
	v_mov_b32_e32 v54, 0
	v_mov_b32_e32 v55, 0
	v_mov_b32_e32 v56, 0
	v_mov_b32_e32 v57, 0
	v_mov_b32_e32 v58, 0
	v_mov_b32_e32 v59, 0
	v_mov_b32_e32 v60, 0
	v_mov_b32_e32 v61, 0
	v_mov_b32_e32 v62, 0
	v_mov_b32_e32 v63, 0
	v_mov_b32_e32 v64, 0
	v_mov_b32_e32 v65, 0
	s_mov_b32 s74, 3
.Lbr_proj_k:
	s_waitcnt vmcnt(8)
	s_barrier
	ds_read_b128 v[208:211], v240 offset:0
	ds_read_b128 v[224:227], v241 offset:0
	ds_read_b128 v[228:231], v241 offset:1024
	ds_read_b128 v[232:235], v241 offset:2048
	ds_read_b128 v[236:239], v241 offset:3072
	s_add_u32 m0, s52, 0xc000
	s_add_u32 s28, s28, 0x40
	s_addc_u32 s29, s29, 0
	global_load_lds_dwordx4 v244, s[28:29]
	global_load_lds_dwordx4 v245, s[28:29] offset:1024
	s_add_u32 m0, s53, 0xc000
	s_add_u32 s30, s30, 0x10000
	s_addc_u32 s31, s31, 0
	global_load_lds_dwordx4 v251, s[30:31]
	global_load_lds_dwordx4 v251, s[30:31] offset:1024
	ds_read_b128 v[212:215], v240 offset:1024
	ds_read_b128 v[216:219], v240 offset:2048
	ds_read_b128 v[220:223], v240 offset:3072
	s_waitcnt lgkmcnt(6)
	v_mfma_f32_16x16x32_bf16 v[2:5], v[224:227], v[208:211], v[2:5]
	s_waitcnt lgkmcnt(5)
	v_mfma_f32_16x16x32_bf16 v[6:9], v[228:231], v[208:211], v[6:9]
	s_waitcnt lgkmcnt(4)
	v_mfma_f32_16x16x32_bf16 v[10:13], v[232:235], v[208:211], v[10:13]
	s_waitcnt lgkmcnt(3)
	v_mfma_f32_16x16x32_bf16 v[14:17], v[236:239], v[208:211], v[14:17]
	s_waitcnt lgkmcnt(2)
	v_mfma_f32_16x16x32_bf16 v[18:21], v[224:227], v[212:215], v[18:21]
	v_mfma_f32_16x16x32_bf16 v[22:25], v[228:231], v[212:215], v[22:25]
	v_mfma_f32_16x16x32_bf16 v[26:29], v[232:235], v[212:215], v[26:29]
	v_mfma_f32_16x16x32_bf16 v[30:33], v[236:239], v[212:215], v[30:33]
	s_waitcnt lgkmcnt(1)
	v_mfma_f32_16x16x32_bf16 v[34:37], v[224:227], v[216:219], v[34:37]
	v_mfma_f32_16x16x32_bf16 v[38:41], v[228:231], v[216:219], v[38:41]
	v_mfma_f32_16x16x32_bf16 v[42:45], v[232:235], v[216:219], v[42:45]
	v_mfma_f32_16x16x32_bf16 v[46:49], v[236:239], v[216:219], v[46:49]
	s_waitcnt lgkmcnt(0)
	v_mfma_f32_16x16x32_bf16 v[50:53], v[224:227], v[220:223], v[50:53]
	v_mfma_f32_16x16x32_bf16 v[54:57], v[228:231], v[220:223], v[54:57]
	v_mfma_f32_16x16x32_bf16 v[58:61], v[232:235], v[220:223], v[58:61]
	v_mfma_f32_16x16x32_bf16 v[62:65], v[236:239], v[220:223], v[62:65]
	s_waitcnt vmcnt(8)
	s_barrier
; #define BLOAD(A_, B_, kt) do { _Pragma("unroll") for (int i = 0; i < 4; ++i) { \
;     A_[i] = *(const u32x4*)((const char*)Ap + (aoff + (unsigned)(32 * i * lda + (kt) * 64) * 2u)); B_[i] = *(const u32x4*)((const char*)Wt + (woff + (unsigned)(32 * i * K + (kt) * 64) * 2u)); } } while (0)
; #define BLOAD(A_, B_, kt) do { _Pragma("unroll") for (int i = 0; i < 4; ++i) { \
;     A_[i] = *(const u32x4*)((const char*)Ap + (aoff + (unsigned)(32 * i * lda + (kt) * 64) * 2u)); B_[i] = *(const u32x4*)((const char*)Wt + (woff + (unsigned)(32 * i * K + (kt) * 64) * 2u)); } } while (0)
; #define BSTORE(A_, B_, buf) do { _Pragma("unroll") for (int i = 0; i < 4; ++i) { \
;     *(u32x4*)&As[(buf) * GBUF + (srow + 32 * i) * LDT + sc8] = A_[i]; \
;     *(u32x4*)&Bs[(buf) * GBUF + (srow + 32 * i) * LDT + sc8] = B_[i]; } } while (0)
; template <bool ROWNORM, int NK>
; DI void gemm_main_bf(const u16* __restrict__ Ap, int lda, const u16* __restrict__ Wt, f32x16 (&acc)[2][2], char* smem, float* rinv_s) {
;     ...
; #pragma unroll
;   for (int kt = 0; kt < nk; kt += 2) {
;     BCOMP(0);
;     BSTORE(a1, b1, 1);
;     if (kt + 3 < nk) BLOAD(a1, b1, kt + 3);
;     __syncthreads();
;     BCOMP(1);
;     if (kt + 2 < nk) { BSTORE(a0, b0, 0); if (kt + 4 < nk) BLOAD(a0, b0, kt + 4); }
;     __syncthreads();
;   }
	ds_read_b128 v[208:211], v240 offset:16384
	ds_read_b128 v[224:227], v241 offset:16384
	ds_read_b128 v[228:231], v241 offset:17408
	ds_read_b128 v[232:235], v241 offset:18432
	ds_read_b128 v[236:239], v241 offset:19456
	s_add_u32 m0, s52, 0x0
	s_add_u32 s28, s28, 0x40
	s_addc_u32 s29, s29, 0
	global_load_lds_dwordx4 v244, s[28:29]
	global_load_lds_dwordx4 v245, s[28:29] offset:1024
	s_add_u32 m0, s53, 0x0
	s_add_u32 s30, s30, 0x10000
	s_addc_u32 s31, s31, 0
	global_load_lds_dwordx4 v251, s[30:31]
	global_load_lds_dwordx4 v251, s[30:31] offset:1024
	ds_read_b128 v[212:215], v240 offset:17408
	ds_read_b128 v[216:219], v240 offset:18432
	ds_read_b128 v[220:223], v240 offset:19456
	s_waitcnt lgkmcnt(6)
	v_mfma_f32_16x16x32_bf16 v[2:5], v[224:227], v[208:211], v[2:5]
	s_waitcnt lgkmcnt(5)
	v_mfma_f32_16x16x32_bf16 v[6:9], v[228:231], v[208:211], v[6:9]
	s_waitcnt lgkmcnt(4)
	v_mfma_f32_16x16x32_bf16 v[10:13], v[232:235], v[208:211], v[10:13]
	s_waitcnt lgkmcnt(3)
	v_mfma_f32_16x16x32_bf16 v[14:17], v[236:239], v[208:211], v[14:17]
	s_waitcnt lgkmcnt(2)
	v_mfma_f32_16x16x32_bf16 v[18:21], v[224:227], v[212:215], v[18:21]
	v_mfma_f32_16x16x32_bf16 v[22:25], v[228:231], v[212:215], v[22:25]
	v_mfma_f32_16x16x32_bf16 v[26:29], v[232:235], v[212:215], v[26:29]
	v_mfma_f32_16x16x32_bf16 v[30:33], v[236:239], v[212:215], v[30:33]
	s_waitcnt lgkmcnt(1)
	v_mfma_f32_16x16x32_bf16 v[34:37], v[224:227], v[216:219], v[34:37]
	v_mfma_f32_16x16x32_bf16 v[38:41], v[228:231], v[216:219], v[38:41]
	v_mfma_f32_16x16x32_bf16 v[42:45], v[232:235], v[216:219], v[42:45]
	v_mfma_f32_16x16x32_bf16 v[46:49], v[236:239], v[216:219], v[46:49]
	s_waitcnt lgkmcnt(0)
	v_mfma_f32_16x16x32_bf16 v[50:53], v[224:227], v[220:223], v[50:53]
	v_mfma_f32_16x16x32_bf16 v[54:57], v[228:231], v[220:223], v[54:57]
	v_mfma_f32_16x16x32_bf16 v[58:61], v[232:235], v[220:223], v[58:61]
	v_mfma_f32_16x16x32_bf16 v[62:65], v[236:239], v[220:223], v[62:65]
	s_waitcnt vmcnt(8)
	s_barrier
	ds_read_b128 v[208:211], v240 offset:32768
	ds_read_b128 v[224:227], v241 offset:32768
	ds_read_b128 v[228:231], v241 offset:33792
	ds_read_b128 v[232:235], v241 offset:34816
	ds_read_b128 v[236:239], v241 offset:35840
	s_add_u32 m0, s52, 0x4000
	s_add_u32 s28, s28, 0x40
	s_addc_u32 s29, s29, 0
	global_load_lds_dwordx4 v244, s[28:29]
	global_load_lds_dwordx4 v245, s[28:29] offset:1024
	s_add_u32 m0, s53, 0x4000
	s_add_u32 s30, s30, 0x10000
	s_addc_u32 s31, s31, 0
	global_load_lds_dwordx4 v251, s[30:31]
	global_load_lds_dwordx4 v251, s[30:31] offset:1024
	ds_read_b128 v[212:215], v240 offset:33792
	ds_read_b128 v[216:219], v240 offset:34816
	ds_read_b128 v[220:223], v240 offset:35840
	s_waitcnt lgkmcnt(6)
	v_mfma_f32_16x16x32_bf16 v[2:5], v[224:227], v[208:211], v[2:5]
	s_waitcnt lgkmcnt(5)
	v_mfma_f32_16x16x32_bf16 v[6:9], v[228:231], v[208:211], v[6:9]
	s_waitcnt lgkmcnt(4)
	v_mfma_f32_16x16x32_bf16 v[10:13], v[232:235], v[208:211], v[10:13]
	s_waitcnt lgkmcnt(3)
	v_mfma_f32_16x16x32_bf16 v[14:17], v[236:239], v[208:211], v[14:17]
	s_waitcnt lgkmcnt(2)
	v_mfma_f32_16x16x32_bf16 v[18:21], v[224:227], v[212:215], v[18:21]
	v_mfma_f32_16x16x32_bf16 v[22:25], v[228:231], v[212:215], v[22:25]
	v_mfma_f32_16x16x32_bf16 v[26:29], v[232:235], v[212:215], v[26:29]
	v_mfma_f32_16x16x32_bf16 v[30:33], v[236:239], v[212:215], v[30:33]
	s_waitcnt lgkmcnt(1)
	v_mfma_f32_16x16x32_bf16 v[34:37], v[224:227], v[216:219], v[34:37]
	v_mfma_f32_16x16x32_bf16 v[38:41], v[228:231], v[216:219], v[38:41]
	v_mfma_f32_16x16x32_bf16 v[42:45], v[232:235], v[216:219], v[42:45]
	v_mfma_f32_16x16x32_bf16 v[46:49], v[236:239], v[216:219], v[46:49]
	s_waitcnt lgkmcnt(0)
	v_mfma_f32_16x16x32_bf16 v[50:53], v[224:227], v[220:223], v[50:53]
	v_mfma_f32_16x16x32_bf16 v[54:57], v[228:231], v[220:223], v[54:57]
	v_mfma_f32_16x16x32_bf16 v[58:61], v[232:235], v[220:223], v[58:61]
	v_mfma_f32_16x16x32_bf16 v[62:65], v[236:239], v[220:223], v[62:65]
	s_waitcnt vmcnt(8)
	s_barrier
	ds_read_b128 v[208:211], v240 offset:49152
	ds_read_b128 v[224:227], v241 offset:49152
	ds_read_b128 v[228:231], v241 offset:50176
	ds_read_b128 v[232:235], v241 offset:51200
	ds_read_b128 v[236:239], v241 offset:52224
	s_add_u32 m0, s52, 0x8000
	s_add_u32 s28, s28, 0x40
	s_addc_u32 s29, s29, 0
	global_load_lds_dwordx4 v244, s[28:29]
	global_load_lds_dwordx4 v245, s[28:29] offset:1024
	s_add_u32 m0, s53, 0x8000
	s_add_u32 s30, s30, 0x10000
	s_addc_u32 s31, s31, 0
	global_load_lds_dwordx4 v251, s[30:31]
	global_load_lds_dwordx4 v251, s[30:31] offset:1024
	ds_read_b128 v[212:215], v240 offset:50176
	ds_read_b128 v[216:219], v240 offset:51200
	ds_read_b128 v[220:223], v240 offset:52224
	s_waitcnt lgkmcnt(6)
	v_mfma_f32_16x16x32_bf16 v[2:5], v[224:227], v[208:211], v[2:5]
	s_waitcnt lgkmcnt(5)
	v_mfma_f32_16x16x32_bf16 v[6:9], v[228:231], v[208:211], v[6:9]
	s_waitcnt lgkmcnt(4)
	v_mfma_f32_16x16x32_bf16 v[10:13], v[232:235], v[208:211], v[10:13]
	s_waitcnt lgkmcnt(3)
	v_mfma_f32_16x16x32_bf16 v[14:17], v[236:239], v[208:211], v[14:17]
	s_waitcnt lgkmcnt(2)
	v_mfma_f32_16x16x32_bf16 v[18:21], v[224:227], v[212:215], v[18:21]
	v_mfma_f32_16x16x32_bf16 v[22:25], v[228:231], v[212:215], v[22:25]
	v_mfma_f32_16x16x32_bf16 v[26:29], v[232:235], v[212:215], v[26:29]
	v_mfma_f32_16x16x32_bf16 v[30:33], v[236:239], v[212:215], v[30:33]
	s_waitcnt lgkmcnt(1)
	v_mfma_f32_16x16x32_bf16 v[34:37], v[224:227], v[216:219], v[34:37]
	v_mfma_f32_16x16x32_bf16 v[38:41], v[228:231], v[216:219], v[38:41]
	v_mfma_f32_16x16x32_bf16 v[42:45], v[232:235], v[216:219], v[42:45]
	v_mfma_f32_16x16x32_bf16 v[46:49], v[236:239], v[216:219], v[46:49]
	s_waitcnt lgkmcnt(0)
	v_mfma_f32_16x16x32_bf16 v[50:53], v[224:227], v[220:223], v[50:53]
	v_mfma_f32_16x16x32_bf16 v[54:57], v[228:231], v[220:223], v[54:57]
	v_mfma_f32_16x16x32_bf16 v[58:61], v[232:235], v[220:223], v[58:61]
	v_mfma_f32_16x16x32_bf16 v[62:65], v[236:239], v[220:223], v[62:65]
	s_sub_u32 s74, s74, 1
	s_cmp_lg_u32 s74, 0
	s_cbranch_scc1 .Lbr_proj_k
; #define BLOAD(A_, B_, kt) do { _Pragma("unroll") for (int i = 0; i < 4; ++i) { \
;     A_[i] = *(const u32x4*)((const char*)Ap + (aoff + (unsigned)(32 * i * lda + (kt) * 64) * 2u)); B_[i] = *(const u32x4*)((const char*)Wt + (woff + (unsigned)(32 * i * K + (kt) * 64) * 2u)); } } while (0)
; #define BLOAD(A_, B_, kt) do { _Pragma("unroll") for (int i = 0; i < 4; ++i) { \
;     A_[i] = *(const u32x4*)((const char*)Ap + (aoff + (unsigned)(32 * i * lda + (kt) * 64) * 2u)); B_[i] = *(const u32x4*)((const char*)Wt + (woff + (unsigned)(32 * i * K + (kt) * 64) * 2u)); } } while (0)
; #define BSTORE(A_, B_, buf) do { _Pragma("unroll") for (int i = 0; i < 4; ++i) { \
;     *(u32x4*)&As[(buf) * GBUF + (srow + 32 * i) * LDT + sc8] = A_[i]; \
;     *(u32x4*)&Bs[(buf) * GBUF + (srow + 32 * i) * LDT + sc8] = B_[i]; } } while (0)
; template <bool ROWNORM, int NK>
; DI void gemm_main_bf(const u16* __restrict__ Ap, int lda, const u16* __restrict__ Wt, f32x16 (&acc)[2][2], char* smem, float* rinv_s) {
;     ...
; #pragma unroll
;   for (int kt = 0; kt < nk; kt += 2) {
;     BCOMP(0);
;     BSTORE(a1, b1, 1);
;     if (kt + 3 < nk) BLOAD(a1, b1, kt + 3);
;     __syncthreads();
;     BCOMP(1);
;     if (kt + 2 < nk) { BSTORE(a0, b0, 0); if (kt + 4 < nk) BLOAD(a0, b0, kt + 4); }
;     __syncthreads();
;   }
	s_waitcnt vmcnt(8)
	s_barrier
	ds_read_b128 v[208:211], v240 offset:0
	ds_read_b128 v[224:227], v241 offset:0
	ds_read_b128 v[228:231], v241 offset:1024
	ds_read_b128 v[232:235], v241 offset:2048
	ds_read_b128 v[236:239], v241 offset:3072
	s_add_u32 m0, s52, 0xc000
	s_add_u32 s28, s28, 0x40
	s_addc_u32 s29, s29, 0
	global_load_lds_dwordx4 v244, s[28:29]
	global_load_lds_dwordx4 v245, s[28:29] offset:1024
	s_add_u32 m0, s53, 0xc000
	s_add_u32 s30, s30, 0x10000
	s_addc_u32 s31, s31, 0
	global_load_lds_dwordx4 v251, s[30:31]
	global_load_lds_dwordx4 v251, s[30:31] offset:1024
	ds_read_b128 v[212:215], v240 offset:1024
	ds_read_b128 v[216:219], v240 offset:2048
	ds_read_b128 v[220:223], v240 offset:3072
	s_waitcnt lgkmcnt(6)
	v_mfma_f32_16x16x32_bf16 v[2:5], v[224:227], v[208:211], v[2:5]
	s_waitcnt lgkmcnt(5)
	v_mfma_f32_16x16x32_bf16 v[6:9], v[228:231], v[208:211], v[6:9]
	s_waitcnt lgkmcnt(4)
	v_mfma_f32_16x16x32_bf16 v[10:13], v[232:235], v[208:211], v[10:13]
	s_waitcnt lgkmcnt(3)
	v_mfma_f32_16x16x32_bf16 v[14:17], v[236:239], v[208:211], v[14:17]
	s_waitcnt lgkmcnt(2)
	v_mfma_f32_16x16x32_bf16 v[18:21], v[224:227], v[212:215], v[18:21]
	v_mfma_f32_16x16x32_bf16 v[22:25], v[228:231], v[212:215], v[22:25]
	v_mfma_f32_16x16x32_bf16 v[26:29], v[232:235], v[212:215], v[26:29]
	v_mfma_f32_16x16x32_bf16 v[30:33], v[236:239], v[212:215], v[30:33]
	s_waitcnt lgkmcnt(1)
	v_mfma_f32_16x16x32_bf16 v[34:37], v[224:227], v[216:219], v[34:37]
	v_mfma_f32_16x16x32_bf16 v[38:41], v[228:231], v[216:219], v[38:41]
	v_mfma_f32_16x16x32_bf16 v[42:45], v[232:235], v[216:219], v[42:45]
	v_mfma_f32_16x16x32_bf16 v[46:49], v[236:239], v[216:219], v[46:49]
	s_waitcnt lgkmcnt(0)
	v_mfma_f32_16x16x32_bf16 v[50:53], v[224:227], v[220:223], v[50:53]
	v_mfma_f32_16x16x32_bf16 v[54:57], v[228:231], v[220:223], v[54:57]
	v_mfma_f32_16x16x32_bf16 v[58:61], v[232:235], v[220:223], v[58:61]
	v_mfma_f32_16x16x32_bf16 v[62:65], v[236:239], v[220:223], v[62:65]
	s_waitcnt vmcnt(8)
	s_barrier
	ds_read_b128 v[208:211], v240 offset:16384
	ds_read_b128 v[224:227], v241 offset:16384
	ds_read_b128 v[228:231], v241 offset:17408
	ds_read_b128 v[232:235], v241 offset:18432
	ds_read_b128 v[236:239], v241 offset:19456
	ds_read_b128 v[212:215], v240 offset:17408
	ds_read_b128 v[216:219], v240 offset:18432
	ds_read_b128 v[220:223], v240 offset:19456
	s_waitcnt lgkmcnt(6)
	v_mfma_f32_16x16x32_bf16 v[2:5], v[224:227], v[208:211], v[2:5]
	s_waitcnt lgkmcnt(5)
	v_mfma_f32_16x16x32_bf16 v[6:9], v[228:231], v[208:211], v[6:9]
	s_waitcnt lgkmcnt(4)
	v_mfma_f32_16x16x32_bf16 v[10:13], v[232:235], v[208:211], v[10:13]
	s_waitcnt lgkmcnt(3)
	v_mfma_f32_16x16x32_bf16 v[14:17], v[236:239], v[208:211], v[14:17]
	s_waitcnt lgkmcnt(2)
	v_mfma_f32_16x16x32_bf16 v[18:21], v[224:227], v[212:215], v[18:21]
	v_mfma_f32_16x16x32_bf16 v[22:25], v[228:231], v[212:215], v[22:25]
	v_mfma_f32_16x16x32_bf16 v[26:29], v[232:235], v[212:215], v[26:29]
	v_mfma_f32_16x16x32_bf16 v[30:33], v[236:239], v[212:215], v[30:33]
	s_waitcnt lgkmcnt(1)
	v_mfma_f32_16x16x32_bf16 v[34:37], v[224:227], v[216:219], v[34:37]
	v_mfma_f32_16x16x32_bf16 v[38:41], v[228:231], v[216:219], v[38:41]
	v_mfma_f32_16x16x32_bf16 v[42:45], v[232:235], v[216:219], v[42:45]
	v_mfma_f32_16x16x32_bf16 v[46:49], v[236:239], v[216:219], v[46:49]
	s_waitcnt lgkmcnt(0)
	v_mfma_f32_16x16x32_bf16 v[50:53], v[224:227], v[220:223], v[50:53]
	v_mfma_f32_16x16x32_bf16 v[54:57], v[228:231], v[220:223], v[54:57]
	v_mfma_f32_16x16x32_bf16 v[58:61], v[232:235], v[220:223], v[58:61]
	v_mfma_f32_16x16x32_bf16 v[62:65], v[236:239], v[220:223], v[62:65]
	s_waitcnt vmcnt(4)
	s_barrier
	ds_read_b128 v[208:211], v240 offset:32768
	ds_read_b128 v[224:227], v241 offset:32768
	ds_read_b128 v[228:231], v241 offset:33792
	ds_read_b128 v[232:235], v241 offset:34816
	ds_read_b128 v[236:239], v241 offset:35840
	ds_read_b128 v[212:215], v240 offset:33792
	ds_read_b128 v[216:219], v240 offset:34816
	ds_read_b128 v[220:223], v240 offset:35840
	s_waitcnt lgkmcnt(6)
	v_mfma_f32_16x16x32_bf16 v[2:5], v[224:227], v[208:211], v[2:5]
	s_waitcnt lgkmcnt(5)
	v_mfma_f32_16x16x32_bf16 v[6:9], v[228:231], v[208:211], v[6:9]
	s_waitcnt lgkmcnt(4)
	v_mfma_f32_16x16x32_bf16 v[10:13], v[232:235], v[208:211], v[10:13]
	s_waitcnt lgkmcnt(3)
	v_mfma_f32_16x16x32_bf16 v[14:17], v[236:239], v[208:211], v[14:17]
	s_waitcnt lgkmcnt(2)
	v_mfma_f32_16x16x32_bf16 v[18:21], v[224:227], v[212:215], v[18:21]
	v_mfma_f32_16x16x32_bf16 v[22:25], v[228:231], v[212:215], v[22:25]
	v_mfma_f32_16x16x32_bf16 v[26:29], v[232:235], v[212:215], v[26:29]
	v_mfma_f32_16x16x32_bf16 v[30:33], v[236:239], v[212:215], v[30:33]
	s_waitcnt lgkmcnt(1)
	v_mfma_f32_16x16x32_bf16 v[34:37], v[224:227], v[216:219], v[34:37]
	v_mfma_f32_16x16x32_bf16 v[38:41], v[228:231], v[216:219], v[38:41]
	v_mfma_f32_16x16x32_bf16 v[42:45], v[232:235], v[216:219], v[42:45]
	v_mfma_f32_16x16x32_bf16 v[46:49], v[236:239], v[216:219], v[46:49]
	s_waitcnt lgkmcnt(0)
	v_mfma_f32_16x16x32_bf16 v[50:53], v[224:227], v[220:223], v[50:53]
	v_mfma_f32_16x16x32_bf16 v[54:57], v[228:231], v[220:223], v[54:57]
	v_mfma_f32_16x16x32_bf16 v[58:61], v[232:235], v[220:223], v[58:61]
	v_mfma_f32_16x16x32_bf16 v[62:65], v[236:239], v[220:223], v[62:65]
	s_waitcnt vmcnt(0)
	s_barrier
; DI unsigned pk2(float a, float b) { f2_t v = {a, b}; bf2_t r = __builtin_convertvector(v, bf2_t); return __builtin_bit_cast(unsigned, r); }
; DI void tile_branch(const Params& p, int l, int tile, char* smem) {
;     ...
; #pragma unroll
;     for (int mt = 0; mt < 2; ++mt)
; #pragma unroll
;       for (int nt = 0; nt < 2; ++nt)
; #pragma unroll
;         for (int i = 0; i < 8; ++i) {
;           const float g0 = __uint_as_float(gpk[mt][nt][i] << 16), g1 = __uint_as_float(gpk[mt][nt][i] & 0xffff0000u);
;           const float a = __uint_as_float(upk[mt][nt][i] << 16) + g0 * acc[mt][nt][2 * i];
;           const float b = __uint_as_float(upk[mt][nt][i] & 0xffff0000u) + g1 * acc[mt][nt][2 * i + 1];
;           upk[mt][nt][i] = pk2(a, b);
;         }
	ds_read_b128 v[208:211], v240 offset:49152
	ds_read_b128 v[224:227], v241 offset:49152
	ds_read_b128 v[228:231], v241 offset:50176
	ds_read_b128 v[232:235], v241 offset:51200
	ds_read_b128 v[236:239], v241 offset:52224
	ds_read_b128 v[212:215], v240 offset:50176
	ds_read_b128 v[216:219], v240 offset:51200
	ds_read_b128 v[220:223], v240 offset:52224
	s_waitcnt lgkmcnt(6)
	v_mfma_f32_16x16x32_bf16 v[2:5], v[224:227], v[208:211], v[2:5]
	s_waitcnt lgkmcnt(5)
	v_mfma_f32_16x16x32_bf16 v[6:9], v[228:231], v[208:211], v[6:9]
	s_waitcnt lgkmcnt(4)
	v_mfma_f32_16x16x32_bf16 v[10:13], v[232:235], v[208:211], v[10:13]
	s_waitcnt lgkmcnt(3)
	v_mfma_f32_16x16x32_bf16 v[14:17], v[236:239], v[208:211], v[14:17]
	s_waitcnt lgkmcnt(2)
	v_mfma_f32_16x16x32_bf16 v[18:21], v[224:227], v[212:215], v[18:21]
	v_mfma_f32_16x16x32_bf16 v[22:25], v[228:231], v[212:215], v[22:25]
	v_mfma_f32_16x16x32_bf16 v[26:29], v[232:235], v[212:215], v[26:29]
	v_mfma_f32_16x16x32_bf16 v[30:33], v[236:239], v[212:215], v[30:33]
	s_waitcnt lgkmcnt(1)
	v_mfma_f32_16x16x32_bf16 v[34:37], v[224:227], v[216:219], v[34:37]
	v_mfma_f32_16x16x32_bf16 v[38:41], v[228:231], v[216:219], v[38:41]
	v_mfma_f32_16x16x32_bf16 v[42:45], v[232:235], v[216:219], v[42:45]
	v_mfma_f32_16x16x32_bf16 v[46:49], v[236:239], v[216:219], v[46:49]
	s_waitcnt lgkmcnt(0)
	v_mfma_f32_16x16x32_bf16 v[50:53], v[224:227], v[220:223], v[50:53]
	v_mfma_f32_16x16x32_bf16 v[54:57], v[228:231], v[220:223], v[54:57]
	v_mfma_f32_16x16x32_bf16 v[58:61], v[232:235], v[220:223], v[58:61]
	v_mfma_f32_16x16x32_bf16 v[62:65], v[236:239], v[220:223], v[62:65]
	s_add_u32 s46, s46, 0x10000
	s_addc_u32 s47, s47, 0
	s_add_u32 s48, s48, 0x1000000
	s_addc_u32 s49, s49, 0
	s_add_u32 s50, s50, 0x100000
	s_addc_u32 s51, s51, 0
	v_lshlrev_b32_e32 v166, 16, v130
	v_and_b32_e32 v167, 0xffff0000, v130
	v_lshlrev_b32_e32 v168, 16, v131
	v_and_b32_e32 v169, 0xffff0000, v131
	v_fmac_f32_e32 v66, v166, v2
	v_fmac_f32_e32 v67, v167, v3
	v_fmac_f32_e32 v68, v168, v4
	v_fmac_f32_e32 v69, v169, v5
	v_lshlrev_b32_e32 v166, 16, v132
	v_and_b32_e32 v167, 0xffff0000, v132
	v_lshlrev_b32_e32 v168, 16, v133
	v_and_b32_e32 v169, 0xffff0000, v133
	v_fmac_f32_e32 v70, v166, v6
	v_fmac_f32_e32 v71, v167, v7
	v_fmac_f32_e32 v72, v168, v8
	v_fmac_f32_e32 v73, v169, v9
	v_lshlrev_b32_e32 v166, 16, v134
	v_and_b32_e32 v167, 0xffff0000, v134
	v_lshlrev_b32_e32 v168, 16, v135
	v_and_b32_e32 v169, 0xffff0000, v135
	v_fmac_f32_e32 v74, v166, v10
	v_fmac_f32_e32 v75, v167, v11
	v_fmac_f32_e32 v76, v168, v12
	v_fmac_f32_e32 v77, v169, v13
	v_lshlrev_b32_e32 v166, 16, v136
	v_and_b32_e32 v167, 0xffff0000, v136
	v_lshlrev_b32_e32 v168, 16, v137
	v_and_b32_e32 v169, 0xffff0000, v137
	v_fmac_f32_e32 v78, v166, v14
	v_fmac_f32_e32 v79, v167, v15
	v_fmac_f32_e32 v80, v168, v16
	v_fmac_f32_e32 v81, v169, v17
	v_lshlrev_b32_e32 v166, 16, v138
	v_and_b32_e32 v167, 0xffff0000, v138
	v_lshlrev_b32_e32 v168, 16, v139
	v_and_b32_e32 v169, 0xffff0000, v139
	v_fmac_f32_e32 v82, v166, v18
	v_fmac_f32_e32 v83, v167, v19
	v_fmac_f32_e32 v84, v168, v20
	v_fmac_f32_e32 v85, v169, v21
	v_lshlrev_b32_e32 v166, 16, v140
	v_and_b32_e32 v167, 0xffff0000, v140
	v_lshlrev_b32_e32 v168, 16, v141
	v_and_b32_e32 v169, 0xffff0000, v141
	v_fmac_f32_e32 v86, v166, v22
	v_fmac_f32_e32 v87, v167, v23
	v_fmac_f32_e32 v88, v168, v24
	v_fmac_f32_e32 v89, v169, v25
	v_lshlrev_b32_e32 v166, 16, v142
	v_and_b32_e32 v167, 0xffff0000, v142
	v_lshlrev_b32_e32 v168, 16, v143
	v_and_b32_e32 v169, 0xffff0000, v143
	v_fmac_f32_e32 v90, v166, v26
	v_fmac_f32_e32 v91, v167, v27
	v_fmac_f32_e32 v92, v168, v28
	v_fmac_f32_e32 v93, v169, v29
	v_lshlrev_b32_e32 v166, 16, v144
	v_and_b32_e32 v167, 0xffff0000, v144
	v_lshlrev_b32_e32 v168, 16, v145
	v_and_b32_e32 v169, 0xffff0000, v145
	v_fmac_f32_e32 v94, v166, v30
	v_fmac_f32_e32 v95, v167, v31
	v_fmac_f32_e32 v96, v168, v32
	v_fmac_f32_e32 v97, v169, v33
	v_lshlrev_b32_e32 v166, 16, v146
	v_and_b32_e32 v167, 0xffff0000, v146
	v_lshlrev_b32_e32 v168, 16, v147
	v_and_b32_e32 v169, 0xffff0000, v147
	v_fmac_f32_e32 v98, v166, v34
	v_fmac_f32_e32 v99, v167, v35
	v_fmac_f32_e32 v100, v168, v36
	v_fmac_f32_e32 v101, v169, v37
	v_lshlrev_b32_e32 v166, 16, v148
	v_and_b32_e32 v167, 0xffff0000, v148
	v_lshlrev_b32_e32 v168, 16, v149
	v_and_b32_e32 v169, 0xffff0000, v149
	v_fmac_f32_e32 v102, v166, v38
	v_fmac_f32_e32 v103, v167, v39
	v_fmac_f32_e32 v104, v168, v40
	v_fmac_f32_e32 v105, v169, v41
	v_lshlrev_b32_e32 v166, 16, v150
	v_and_b32_e32 v167, 0xffff0000, v150
	v_lshlrev_b32_e32 v168, 16, v151
	v_and_b32_e32 v169, 0xffff0000, v151
	v_fmac_f32_e32 v106, v166, v42
	v_fmac_f32_e32 v107, v167, v43
	v_fmac_f32_e32 v108, v168, v44
	v_fmac_f32_e32 v109, v169, v45
	v_lshlrev_b32_e32 v166, 16, v152
	v_and_b32_e32 v167, 0xffff0000, v152
	v_lshlrev_b32_e32 v168, 16, v153
	v_and_b32_e32 v169, 0xffff0000, v153
	v_fmac_f32_e32 v110, v166, v46
	v_fmac_f32_e32 v111, v167, v47
	v_fmac_f32_e32 v112, v168, v48
	v_fmac_f32_e32 v113, v169, v49
	v_lshlrev_b32_e32 v166, 16, v154
	v_and_b32_e32 v167, 0xffff0000, v154
	v_lshlrev_b32_e32 v168, 16, v155
	v_and_b32_e32 v169, 0xffff0000, v155
	v_fmac_f32_e32 v114, v166, v50
	v_fmac_f32_e32 v115, v167, v51
	v_fmac_f32_e32 v116, v168, v52
	v_fmac_f32_e32 v117, v169, v53
	v_lshlrev_b32_e32 v166, 16, v156
	v_and_b32_e32 v167, 0xffff0000, v156
	v_lshlrev_b32_e32 v168, 16, v157
	v_and_b32_e32 v169, 0xffff0000, v157
	v_fmac_f32_e32 v118, v166, v54
	v_fmac_f32_e32 v119, v167, v55
	v_fmac_f32_e32 v120, v168, v56
	v_fmac_f32_e32 v121, v169, v57
	v_lshlrev_b32_e32 v166, 16, v158
	v_and_b32_e32 v167, 0xffff0000, v158
	v_lshlrev_b32_e32 v168, 16, v159
	v_and_b32_e32 v169, 0xffff0000, v159
	v_fmac_f32_e32 v122, v166, v58
	v_fmac_f32_e32 v123, v167, v59
	v_fmac_f32_e32 v124, v168, v60
	v_fmac_f32_e32 v125, v169, v61
	v_lshlrev_b32_e32 v166, 16, v160
	v_and_b32_e32 v167, 0xffff0000, v160
	v_lshlrev_b32_e32 v168, 16, v161
	v_and_b32_e32 v169, 0xffff0000, v161
	v_fmac_f32_e32 v126, v166, v62
	v_fmac_f32_e32 v127, v167, v63
	v_fmac_f32_e32 v128, v168, v64
	v_fmac_f32_e32 v129, v169, v65
	s_cmp_eq_u32 s75, 2
	s_cbranch_scc1 .Lbr_noprol
; DI int crow(int r, int hi) { return (r & 3) + 8 * (r >> 2) + 4 * hi; }
; DI void st8(u16* dst, const float (&v)[8]) { *(u32x4*)dst = pack8(v); }
; DI void tile_branch(const Params& p, int l, int tile, char* smem) {
;     ...
;   for (int br = 0; br < 3; ++br) {
;     ...
;   __syncthreads();
; #pragma unroll
;   for (int mt = 0; mt < 2; ++mt)
; #pragma unroll
;     for (int nt = 0; nt < 2; ++nt)
; #pragma unroll
;       for (int i = 0; i < 8; ++i) {
;         const int cc = wn * 64 + nt * 32 + r32;
;         Cs[(wm * 64 + mt * 32 + crow(2 * i, hi)) * CSL + cc] = __uint_as_float(upk[mt][nt][i] << 16);
;         Cs[(wm * 64 + mt * 32 + crow(2 * i + 1, hi)) * CSL + cc] = __uint_as_float(upk[mt][nt][i] & 0xffff0000u);
;       }
;   __syncthreads();
;   const int row = tid >> 1, half = tid & 1; float v[8];
;   u16* dst = (u16*)(p.ws + OFF_U) + (size_t)(m0 + row) * 1024 + n0 + half * 64;
; #pragma unroll
;   for (int c8 = 0; c8 < 8; ++c8) { cs_ld8(Cs, row, half * 64 + c8 * 8, v); st8(dst + c8 * 8, v); }
	s_mov_b64 s[28:29], s[44:45]
	s_mov_b64 s[30:31], s[46:47]
	s_add_u32 m0, s52, 0x0
	s_nop 0
	global_load_lds_dwordx4 v251, s[28:29]
	global_load_lds_dwordx4 v251, s[28:29] offset:1024
	s_add_u32 m0, s53, 0x0
	s_nop 0
	global_load_lds_dwordx4 v251, s[30:31]
	global_load_lds_dwordx4 v251, s[30:31] offset:1024
	s_add_u32 m0, s52, 0x4000
	s_add_u32 s28, s28, 0x100000
	s_addc_u32 s29, s29, 0
	global_load_lds_dwordx4 v251, s[28:29]
	global_load_lds_dwordx4 v251, s[28:29] offset:1024
	s_add_u32 m0, s53, 0x4000
	s_add_u32 s30, s30, 0x30000
	s_addc_u32 s31, s31, 0
	global_load_lds_dwordx4 v251, s[30:31]
	global_load_lds_dwordx4 v251, s[30:31] offset:1024
	s_add_u32 m0, s52, 0x8000
	s_add_u32 s28, s28, 0x100000
	s_addc_u32 s29, s29, 0
	global_load_lds_dwordx4 v251, s[28:29]
	global_load_lds_dwordx4 v251, s[28:29] offset:1024
	s_add_u32 m0, s53, 0x8000
	s_add_u32 s30, s30, 0x30000
	s_addc_u32 s31, s31, 0
	global_load_lds_dwordx4 v251, s[30:31]
	global_load_lds_dwordx4 v251, s[30:31] offset:1024
.Lbr_noprol:
	s_add_i32 s75, s75, 1
	s_cmp_lt_u32 s75, 3
	s_cbranch_scc1 .Lbr_loop
	v_add_u32_e32 v170, 0x100000, v249
	v_cvt_pk_bf16_f32 v66, v66, v67
	v_cvt_pk_bf16_f32 v67, v68, v69
	global_store_dwordx2 v249, v[66:67], s[22:23]
	v_cvt_pk_bf16_f32 v70, v70, v71
	v_cvt_pk_bf16_f32 v71, v72, v73
	global_store_dwordx2 v249, v[70:71], s[22:23] offset:32
	v_cvt_pk_bf16_f32 v74, v74, v75
	v_cvt_pk_bf16_f32 v75, v76, v77
	global_store_dwordx2 v170, v[74:75], s[22:23]
	v_cvt_pk_bf16_f32 v78, v78, v79
	v_cvt_pk_bf16_f32 v79, v80, v81
	global_store_dwordx2 v170, v[78:79], s[22:23] offset:32
	v_cvt_pk_bf16_f32 v82, v82, v83
	v_cvt_pk_bf16_f32 v83, v84, v85
	global_store_dwordx2 v249, v[82:83], s[22:23] offset:1024
	v_cvt_pk_bf16_f32 v86, v86, v87
	v_cvt_pk_bf16_f32 v87, v88, v89
	global_store_dwordx2 v249, v[86:87], s[22:23] offset:1056
	v_cvt_pk_bf16_f32 v90, v90, v91
	v_cvt_pk_bf16_f32 v91, v92, v93
	global_store_dwordx2 v170, v[90:91], s[22:23] offset:1024
	v_cvt_pk_bf16_f32 v94, v94, v95
	v_cvt_pk_bf16_f32 v95, v96, v97
	global_store_dwordx2 v170, v[94:95], s[22:23] offset:1056
	v_cvt_pk_bf16_f32 v98, v98, v99
	v_cvt_pk_bf16_f32 v99, v100, v101
	global_store_dwordx2 v249, v[98:99], s[22:23] offset:2048
	v_cvt_pk_bf16_f32 v102, v102, v103
	v_cvt_pk_bf16_f32 v103, v104, v105
	global_store_dwordx2 v249, v[102:103], s[22:23] offset:2080
	v_cvt_pk_bf16_f32 v106, v106, v107
	v_cvt_pk_bf16_f32 v107, v108, v109
	global_store_dwordx2 v170, v[106:107], s[22:23] offset:2048
	v_cvt_pk_bf16_f32 v110, v110, v111
	v_cvt_pk_bf16_f32 v111, v112, v113
	global_store_dwordx2 v170, v[110:111], s[22:23] offset:2080
	v_cvt_pk_bf16_f32 v114, v114, v115
	v_cvt_pk_bf16_f32 v115, v116, v117
	global_store_dwordx2 v249, v[114:115], s[22:23] offset:3072
	v_cvt_pk_bf16_f32 v118, v118, v119
	v_cvt_pk_bf16_f32 v119, v120, v121
	global_store_dwordx2 v249, v[118:119], s[22:23] offset:3104
	v_cvt_pk_bf16_f32 v122, v122, v123
	v_cvt_pk_bf16_f32 v123, v124, v125
	global_store_dwordx2 v170, v[122:123], s[22:23] offset:3072
	v_cvt_pk_bf16_f32 v126, v126, v127
	v_cvt_pk_bf16_f32 v127, v128, v129
	global_store_dwordx2 v170, v[126:127], s[22:23] offset:3104
	s_add_i32 s17, s17, s78
	s_add_i32 s43, s43, s95
	s_cmpk_gt_i32 s17, 0x3ff
	s_cbranch_scc0 .LBB1_262
